# v25 with hgrn head start of 10 chunks (was 7) during gdnpre
# speedup vs baseline: 1.0021x; 1.0021x over previous
.Lhs_p3:
	s_movk_i32 s101, 10
	s_cmp_lt_u32 s62, 64
	s_cbranch_scc1 .Lhs_done
	s_sub_u32 s64, s62, 64
	s_movk_i32 s75, 0xc0
